# P2 conversion loop: counted wait relaxed to vmcnt(24) so the previous item's stores need not be acknowledged before the next transpose (one drain before the loop keeps the first iteration exact)
# speedup vs baseline: 1.0046x; 1.0046x over previous
; #define LAS __attribute__((address_space(3)))
; #define KIN(i) ((const float*)karg(i))
; __device__ __forceinline__ void tr_load(const ItemD& d, int lane, f32x4 (&v)[16]) {
;     const float* src = d.W + (size_t)(lane >> 4) * d.ldw + (lane & 15) * 4;
; #pragma unroll
;     for (int i = 0; i < 16; ++i) v[i] = *(const f32x4*)(src + (size_t)(4 * i) * d.ldw);
; }
; __device__ __forceinline__ ItemD decode_item(int it) {
;     unsigned char* ws = KWS;
;     int r = it;
;     if (r < I_IN) { const int kb = r >> 7, nb = r & 127, n0 = nb * 64, seg = n0 >> 11; const int dseg = seg == 2 ? 3 : (seg == 3 ? 2 : seg);
;         return mk_item(KIN(5), 8192, kb * 64, n0, (bf16_t*)(ws + WS_WIN), DM, dseg * 2048 + (n0 & 2047)); }
;     r -= I_IN;
;     if (r < I_OUT) { const int kb = r >> 6, nb = r & 63; return mk_item(KIN(9), DM, kb * 64, nb * 64, (bf16_t*)(ws + WS_WOUT), DM, nb * 64); }
;     r -= I_OUT;
;     if (r < 2 * I_G) { const int up = r >= I_G; if (up) r -= I_G; const int kb = r / 172, nb = r % 172, n0 = nb * 64;
;         return mk_item(KIN(up ? 13 : 12), DFF, kb * 64, n0, (bf16_t*)(ws + WS_WGU), DM, (n0 >> 7) * 256 + (n0 & 127) + (up ? 128 : 0)); }
;     r -= 2 * I_G;
;     if (r < I_DN) { const int kb = r >> 6, nb = r & 63; return mk_item(KIN(14), DM, kb * 64, nb * 64, (bf16_t*)(ws + WS_WDOWN), DFF, nb * 64); }
;     r -= I_DN;
;     { const int g = r >> 6, rr = r & 63, kb = rr >> 3, nb = rr & 7;
;       return mk_item(KIN(7) + (size_t)g * 512 * 512, 512, kb * 64, nb * 64, (bf16_t*)(ws + WS_WPOOL) + (size_t)g * 512 * 512, 512, nb * 64); }
; }
; __device__ __forceinline__ void convert_items(LAS float* scr, int lane, int it_lo, int it_hi, int cw, int ncw) {
;     asm volatile("" : "+v"(lane));
;     int it = it_lo + cw; if (it >= it_hi) return;
;     ItemD d0 = decode_item(it), d1 = d0; f32x4 v0[16], v1[16];
;     tr_load(d0, lane, v0);
;     for (;;) {
;         it += ncw; const bool h1 = it < it_hi;
;         if (h1) { d1 = decode_item(it); tr_load(d1, lane, v1); }
.LBB0_462:
	s_and_b32 s10, 0xffff, s22
	s_cmp_lg_u32 s10, 0
	s_cselect_b64 s[10:11], -1, 0
	s_cmp_lg_u64 s[10:11], 0
	s_addc_u32 s62, s44, 0
	s_lshl_b64 s[10:11], s[12:13], 1
	s_add_u32 s12, s14, s10
	s_addc_u32 s14, s15, s11
	s_lshl_b64 s[10:11], s[76:77], 1
	v_ashrrev_i32_e32 v128, 4, v64
	s_add_u32 s10, s12, s10
	v_ashrrev_i32_e32 v129, 31, v128
	s_addc_u32 s11, s14, s11
	v_mul_lo_u32 v2, s74, v129
	v_mul_lo_u32 v3, s75, v128
	v_mad_u64_u32 v[0:1], s[14:15], s74, v128, 0
	v_add3_u32 v1, v1, v2, v3
	v_lshlrev_b32_e32 v2, 2, v64
	v_and_b32_e32 v130, 60, v2
	v_lshl_add_u64 v[0:1], v[0:1], 2, s[72:73]
	v_lshlrev_b32_e32 v160, 2, v130
	v_lshl_add_u64 v[0:1], v[0:1], 0, v[160:161]
	s_lshl_b64 s[14:15], s[74:75], 4
	v_lshl_add_u64 v[8:9], v[0:1], 0, s[14:15]
	global_load_dwordx4 v[0:3], v[0:1], off
	s_nop 0
	global_load_dwordx4 v[4:7], v[8:9], off
	v_lshl_add_u64 v[8:9], v[8:9], 0, s[14:15]
	v_lshl_add_u64 v[16:17], v[8:9], 0, s[14:15]
	global_load_dwordx4 v[8:11], v[8:9], off
	s_nop 0
	global_load_dwordx4 v[12:15], v[16:17], off
	v_lshl_add_u64 v[16:17], v[16:17], 0, s[14:15]
	v_lshl_add_u64 v[24:25], v[16:17], 0, s[14:15]
	global_load_dwordx4 v[16:19], v[16:17], off
	s_nop 0
	global_load_dwordx4 v[20:23], v[24:25], off
	v_lshl_add_u64 v[24:25], v[24:25], 0, s[14:15]
	v_lshl_add_u64 v[32:33], v[24:25], 0, s[14:15]
	v_lshl_add_u64 v[36:37], v[32:33], 0, s[14:15]
	v_lshl_add_u64 v[40:41], v[36:37], 0, s[14:15]
	v_lshl_add_u64 v[44:45], v[40:41], 0, s[14:15]
	v_lshl_add_u64 v[48:49], v[44:45], 0, s[14:15]
	v_lshl_add_u64 v[52:53], v[48:49], 0, s[14:15]
	v_lshl_add_u64 v[56:57], v[52:53], 0, s[14:15]
	v_lshl_add_u64 v[60:61], v[56:57], 0, s[14:15]
	global_load_dwordx4 v[24:27], v[24:25], off
	s_nop 0
	global_load_dwordx4 v[28:31], v[32:33], off
	v_ashrrev_i32_e32 v132, 3, v64
	global_load_dwordx4 v[32:35], v[36:37], off
	v_lshlrev_b32_e32 v64, 3, v64
	global_load_dwordx4 v[36:39], v[40:41], off
	v_and_b32_e32 v134, 56, v64
	global_load_dwordx4 v[40:43], v[44:45], off
	s_mul_i32 s12, s62, 3
	global_load_dwordx4 v[44:47], v[48:49], off
	v_mul_u32_u24_e32 v64, 0x104, v134
	global_load_dwordx4 v[48:51], v[52:53], off
	v_lshlrev_b32_e32 v67, 2, v132
	global_load_dwordx4 v[52:55], v[56:57], off
	v_add_u32_e32 v136, 8, v132
	global_load_dwordx4 v[56:59], v[60:61], off
	v_lshl_add_u64 v[60:61], v[60:61], 0, s[14:15]
	global_load_dwordx4 v[60:63], v[60:61], off
	s_movk_i32 s14, 0x104
	v_readlane_b32 s15, v250, 15
	v_mul_lo_u32 v66, v128, s14
	v_readlane_b32 s14, v250, 0
	v_add_u32_e32 v65, s15, v160
	v_add3_u32 v172, s15, v64, v67
	v_add_u32_e32 v138, 16, v132
	v_add_u32_e32 v140, 24, v132
	v_add_u32_e32 v142, 32, v132
	v_add_u32_e32 v162, 40, v132
	v_add_u32_e32 v164, 48, v132
	v_add_u32_e32 v166, 56, v132
	s_mul_i32 s33, s62, 6
	s_mul_i32 s89, s62, 48
	v_readlane_b32 s15, v250, 21
	s_add_i32 s23, s14, s12
	s_mul_i32 s12, s62, 24
	v_ashrrev_i32_e32 v131, 31, v132
	v_ashrrev_i32_e32 v133, 31, v136
	v_ashrrev_i32_e32 v135, 31, v138
	v_ashrrev_i32_e32 v137, 31, v140
	v_ashrrev_i32_e32 v139, 31, v142
	v_ashrrev_i32_e32 v141, 31, v162
	v_ashrrev_i32_e32 v143, 31, v164
	v_ashrrev_i32_e32 v163, 31, v166
	s_add_i32 s88, s14, s33
	s_add_i32 s39, s15, s89
	s_mul_i32 s22, s62, 0x180
	s_add_i32 s35, s15, s12
	s_mulk_i32 s62, 0xc0
	v_add_u32_e32 v173, v65, v66
	v_readlane_b32 s63, v250, 25
	v_readlane_b32 s94, v250, 23
	s_mov_b32 s97, s5
	s_mov_b64 s[14:15], s[10:11]
	s_waitcnt vmcnt(0)
	s_branch .LBB0_466
.LBB0_463:
	s_waitcnt lgkmcnt(0)
	s_lshl_b64 s[10:11], s[12:13], 1
	s_add_u32 s12, s72, s10
	s_addc_u32 s72, s73, s11
	s_lshl_b64 s[10:11], s[76:77], 1
	s_add_u32 s10, s12, s10
	s_addc_u32 s11, s72, s11
	v_mul_lo_u32 v2, s79, v128
	v_mul_lo_u32 v3, s78, v129
	v_mad_u64_u32 v[0:1], s[72:73], s78, v128, 0
	v_add3_u32 v1, v1, v3, v2
	v_lshl_add_u64 v[0:1], v[0:1], 2, s[74:75]
	v_lshlrev_b32_e32 v2, 2, v130
	v_mov_b32_e32 v3, v161
	v_lshl_add_u64 v[0:1], v[0:1], 0, v[2:3]
	s_lshl_b64 s[72:73], s[78:79], 4
	v_lshl_add_u64 v[8:9], v[0:1], 0, s[72:73]
	global_load_dwordx4 v[0:3], v[0:1], off
	s_nop 0
	global_load_dwordx4 v[4:7], v[8:9], off
	v_lshl_add_u64 v[8:9], v[8:9], 0, s[72:73]
	v_lshl_add_u64 v[16:17], v[8:9], 0, s[72:73]
	global_load_dwordx4 v[8:11], v[8:9], off
	s_nop 0
	global_load_dwordx4 v[12:15], v[16:17], off
	v_lshl_add_u64 v[16:17], v[16:17], 0, s[72:73]
	v_lshl_add_u64 v[24:25], v[16:17], 0, s[72:73]
	global_load_dwordx4 v[16:19], v[16:17], off
	s_nop 0
	global_load_dwordx4 v[20:23], v[24:25], off
	v_lshl_add_u64 v[24:25], v[24:25], 0, s[72:73]
	v_lshl_add_u64 v[32:33], v[24:25], 0, s[72:73]
	v_lshl_add_u64 v[36:37], v[32:33], 0, s[72:73]
	v_lshl_add_u64 v[40:41], v[36:37], 0, s[72:73]
	v_lshl_add_u64 v[44:45], v[40:41], 0, s[72:73]
	v_lshl_add_u64 v[48:49], v[44:45], 0, s[72:73]
	v_lshl_add_u64 v[52:53], v[48:49], 0, s[72:73]
	v_lshl_add_u64 v[56:57], v[52:53], 0, s[72:73]
	v_lshl_add_u64 v[60:61], v[56:57], 0, s[72:73]
	global_load_dwordx4 v[24:27], v[24:25], off
	s_nop 0
	global_load_dwordx4 v[28:31], v[32:33], off
	s_nop 0
	global_load_dwordx4 v[32:35], v[36:37], off
	s_nop 0
	global_load_dwordx4 v[36:39], v[40:41], off
	s_nop 0
	global_load_dwordx4 v[40:43], v[44:45], off
	s_nop 0
	global_load_dwordx4 v[44:47], v[48:49], off
	s_nop 0
	global_load_dwordx4 v[48:51], v[52:53], off
	s_nop 0
	global_load_dwordx4 v[52:55], v[56:57], off
	s_nop 0
	global_load_dwordx4 v[56:59], v[60:61], off
	v_lshl_add_u64 v[60:61], v[60:61], 0, s[72:73]
	global_load_dwordx4 v[60:63], v[60:61], off
	s_waitcnt vmcnt(24)
	s_branch .LBB0_464

; __device__ __forceinline__ void tr_load(const ItemD& d, int lane, f32x4 (&v)[16]) {
;     const float* src = d.W + (size_t)(lane >> 4) * d.ldw + (lane & 15) * 4;
; #pragma unroll
;     for (int i = 0; i < 16; ++i) v[i] = *(const f32x4*)(src + (size_t)(4 * i) * d.ldw);
; }
; __device__ __forceinline__ void convert_items(LAS float* scr, int lane, int it_lo, int it_hi, int cw, int ncw) {
;     ...
;     for (;;) {
;         it += ncw; const bool h1 = it < it_hi;
;         if (h1) { d1 = decode_item(it); tr_load(d1, lane, v1); }
;         tr_store(d0, lane, v0, scr);
;         if (!h1) break;
;         it += ncw; const bool h0 = it < it_hi;
;         if (h0) { d0 = decode_item(it); tr_load(d0, lane, v0); }
;         tr_store(d1, lane, v1, scr);
.LBB0_482:
	s_waitcnt lgkmcnt(0)
	s_lshl_b64 s[14:15], s[12:13], 1
	s_add_u32 s12, s74, s14
	s_addc_u32 s74, s75, s15
	s_lshl_b64 s[14:15], s[78:79], 1
	s_add_u32 s14, s12, s14
	s_addc_u32 s15, s74, s15
	v_mul_lo_u32 v66, s81, v128
	v_mul_lo_u32 v67, s80, v129
	v_mad_u64_u32 v[64:65], s[74:75], s80, v128, 0
	v_add3_u32 v65, v65, v67, v66
	v_lshl_add_u64 v[64:65], v[64:65], 2, s[76:77]
	v_lshlrev_b32_e32 v160, 2, v130
	v_lshl_add_u64 v[64:65], v[64:65], 0, v[160:161]
	s_lshl_b64 s[74:75], s[80:81], 4
	v_lshl_add_u64 v[72:73], v[64:65], 0, s[74:75]
	global_load_dwordx4 v[68:71], v[64:65], off
	s_nop 0
	global_load_dwordx4 v[64:67], v[72:73], off
	v_lshl_add_u64 v[72:73], v[72:73], 0, s[74:75]
	v_lshl_add_u64 v[80:81], v[72:73], 0, s[74:75]
	global_load_dwordx4 v[76:79], v[72:73], off
	s_nop 0
	global_load_dwordx4 v[72:75], v[80:81], off
	v_lshl_add_u64 v[80:81], v[80:81], 0, s[74:75]
	v_lshl_add_u64 v[88:89], v[80:81], 0, s[74:75]
	global_load_dwordx4 v[84:87], v[80:81], off
	s_nop 0
	global_load_dwordx4 v[80:83], v[88:89], off
	v_lshl_add_u64 v[88:89], v[88:89], 0, s[74:75]
	v_lshl_add_u64 v[96:97], v[88:89], 0, s[74:75]
	v_lshl_add_u64 v[100:101], v[96:97], 0, s[74:75]
	v_lshl_add_u64 v[104:105], v[100:101], 0, s[74:75]
	v_lshl_add_u64 v[108:109], v[104:105], 0, s[74:75]
	v_lshl_add_u64 v[112:113], v[108:109], 0, s[74:75]
	v_lshl_add_u64 v[116:117], v[112:113], 0, s[74:75]
	v_lshl_add_u64 v[120:121], v[116:117], 0, s[74:75]
	v_lshl_add_u64 v[124:125], v[120:121], 0, s[74:75]
	global_load_dwordx4 v[92:95], v[88:89], off
	s_nop 0
	global_load_dwordx4 v[88:91], v[96:97], off
	s_nop 0
	global_load_dwordx4 v[96:99], v[100:101], off
	s_nop 0
	global_load_dwordx4 v[100:103], v[104:105], off
	s_nop 0
	global_load_dwordx4 v[104:107], v[108:109], off
	s_nop 0
	global_load_dwordx4 v[108:111], v[112:113], off
	s_nop 0
	global_load_dwordx4 v[112:115], v[116:117], off
	s_nop 0
	global_load_dwordx4 v[116:119], v[120:121], off
	s_nop 0
	global_load_dwordx4 v[120:123], v[124:125], off
	v_lshl_add_u64 v[124:125], v[124:125], 0, s[74:75]
	global_load_dwordx4 v[124:127], v[124:125], off
	s_waitcnt vmcnt(24)
	s_branch .LBB0_483
